# v51 + mixer-in rows_rstd16 (one site): vmcnt(0) between the two partial-sum load groups moved behind the second group as vmcnt(18)
# baseline (speedup 1.0000x reference)
.LBB0_588:
	v_lshl_add_u32 v179, s42, 8, v174
	v_add_u32_e32 v48, v179, v176
	v_add_u32_e32 v144, 0x4000, v48
	v_mov_b32_e32 v145, v49
	v_add_u32_e32 v146, 0x8000, v48
	v_mov_b32_e32 v147, v49
	v_add_u32_e32 v150, 0x4020, v48
	v_mov_b32_e32 v151, v49
	v_add_u32_e32 v158, 0x4030, v48
	v_mov_b32_e32 v159, v49
	v_lshl_add_u64 v[142:143], v[48:49], 2, s[22:23]
	v_lshl_add_u64 v[144:145], v[144:145], 2, s[22:23]
	v_lshl_add_u64 v[146:147], v[146:147], 2, s[22:23]
	v_lshl_add_u64 v[150:151], v[150:151], 2, s[22:23]
	v_lshl_add_u64 v[158:159], v[158:159], 2, s[22:23]
	global_load_dword v142, v[142:143], off
	s_movk_i32 s6, 0x600
	global_load_dword v144, v[144:145], off
	s_cmp_lt_i32 s44, 1
	global_load_dword v152, v[150:151], off
	global_load_dword v143, v[146:147], off
	global_load_dword v160, v[158:159], off
	v_add_u32_e32 v146, 0xc000, v48
	v_mov_b32_e32 v147, v49
	v_lshl_add_u64 v[146:147], v[146:147], 2, s[22:23]
	global_load_dword v145, v[146:147], off
	v_or_b32_e32 v146, 16, v48
	v_mov_b32_e32 v147, v49
	v_lshl_add_u64 v[146:147], v[146:147], 2, s[22:23]
	global_load_dword v148, v[146:147], off
	v_add_u32_e32 v146, 0x4010, v48
	v_mov_b32_e32 v147, v49
	v_lshl_add_u64 v[146:147], v[146:147], 2, s[22:23]
	global_load_dword v156, v[146:147], off
	v_add_u32_e32 v146, 0x8010, v48
	v_mov_b32_e32 v147, v49
	v_lshl_add_u64 v[146:147], v[146:147], 2, s[22:23]
	global_load_dword v149, v[146:147], off
	v_add_u32_e32 v146, 0xc010, v48
	v_mov_b32_e32 v147, v49
	v_lshl_add_u64 v[146:147], v[146:147], 2, s[22:23]
	global_load_dword v157, v[146:147], off
	v_or_b32_e32 v146, 32, v48
	v_mov_b32_e32 v147, v49
	v_add_u32_e32 v150, 0x8020, v48
	v_mov_b32_e32 v151, v49
	v_lshl_add_u64 v[146:147], v[146:147], 2, s[22:23]
	v_lshl_add_u64 v[150:151], v[150:151], 2, s[22:23]
	global_load_dword v146, v[146:147], off
	v_add_u32_e32 v158, 0x8030, v48
	global_load_dword v147, v[150:151], off
	v_add_u32_e32 v150, 0xc020, v48
	v_mov_b32_e32 v151, v49
	v_lshl_add_u64 v[150:151], v[150:151], 2, s[22:23]
	global_load_dword v153, v[150:151], off
	v_or_b32_e32 v150, 48, v48
	v_mov_b32_e32 v151, v49
	v_mov_b32_e32 v159, v49
	v_lshl_add_u64 v[150:151], v[150:151], 2, s[22:23]
	v_lshl_add_u64 v[158:159], v[158:159], 2, s[22:23]
	global_load_dword v150, v[150:151], off
	global_load_dword v151, v[158:159], off
	v_add_u32_e32 v158, 0xc030, v48
	v_mov_b32_e32 v159, v49
	v_lshl_add_u64 v[158:159], v[158:159], 2, s[22:23]
	global_load_dword v161, v[158:159], off
	v_add_u32_e32 v158, 0x80, v48
	v_mov_b32_e32 v159, v49
	v_lshl_add_u64 v[158:159], v[158:159], 2, s[22:23]
	global_load_dword v162, v[158:159], off
	v_add_u32_e32 v158, 0x4080, v48
	v_mov_b32_e32 v159, v49
	v_lshl_add_u64 v[158:159], v[158:159], 2, s[22:23]
	global_load_dword v166, v[158:159], off
	v_add_u32_e32 v158, 0x8080, v48
	v_mov_b32_e32 v159, v49
	v_lshl_add_u64 v[158:159], v[158:159], 2, s[22:23]
	global_load_dword v163, v[158:159], off
	v_add_u32_e32 v158, 0xc080, v48
	v_mov_b32_e32 v159, v49
	v_lshl_add_u64 v[158:159], v[158:159], 2, s[22:23]
	global_load_dword v167, v[158:159], off
	v_add_u32_e32 v158, 0x90, v48
	v_mov_b32_e32 v159, v49
	v_lshl_add_u64 v[158:159], v[158:159], 2, s[22:23]
	global_load_dword v164, v[158:159], off
	v_add_u32_e32 v158, 0x4090, v48
	v_mov_b32_e32 v159, v49
	v_lshl_add_u64 v[158:159], v[158:159], 2, s[22:23]
	global_load_dword v168, v[158:159], off
	v_add_u32_e32 v158, 0x8090, v48
	v_mov_b32_e32 v159, v49
	v_lshl_add_u64 v[158:159], v[158:159], 2, s[22:23]
	global_load_dword v165, v[158:159], off
	v_add_u32_e32 v158, 0xc090, v48
	v_mov_b32_e32 v159, v49
	v_lshl_add_u64 v[158:159], v[158:159], 2, s[22:23]
	global_load_dword v169, v[158:159], off
	v_add_u32_e32 v158, 0xa0, v48
	v_mov_b32_e32 v159, v49
	v_lshl_add_u64 v[158:159], v[158:159], 2, s[22:23]
	global_load_dword v170, v[158:159], off
	v_add_u32_e32 v158, 0x40a0, v48
	v_mov_b32_e32 v159, v49
	v_lshl_add_u64 v[158:159], v[158:159], 2, s[22:23]
	global_load_dword v172, v[158:159], off
	v_add_u32_e32 v158, 0x80a0, v48
	v_mov_b32_e32 v159, v49
	v_lshl_add_u64 v[158:159], v[158:159], 2, s[22:23]
	global_load_dword v171, v[158:159], off
	v_add_u32_e32 v158, 0xc0a0, v48
	v_mov_b32_e32 v159, v49
	v_lshl_add_u64 v[158:159], v[158:159], 2, s[22:23]
	global_load_dword v173, v[158:159], off
	v_add_u32_e32 v158, 0xb0, v48
	v_mov_b32_e32 v159, v49
	v_lshl_add_u64 v[158:159], v[158:159], 2, s[22:23]
	global_load_dword v182, v[158:159], off
	v_add_u32_e32 v158, 0x40b0, v48
	v_mov_b32_e32 v159, v49
	v_lshl_add_u64 v[158:159], v[158:159], 2, s[22:23]
	global_load_dword v184, v[158:159], off
	v_add_u32_e32 v158, 0x80b0, v48
	v_mov_b32_e32 v159, v49
	v_lshl_add_u64 v[158:159], v[158:159], 2, s[22:23]
	v_add_u32_e32 v48, 0xc0b0, v48
	global_load_dword v183, v[158:159], off
	v_lshl_add_u64 v[158:159], v[48:49], 2, s[22:23]
	global_load_dword v185, v[158:159], off
	s_waitcnt vmcnt(18)
	v_pk_add_f32 v[142:143], v[142:143], v[144:145]
	v_and_b32_e32 v158, 64, v205
	v_xor_b32_e32 v48, 16, v205
	v_add_u32_e32 v158, 64, v158
	v_cmp_lt_i32_e32 vcc, v48, v158
	v_pk_add_f32 v[148:149], v[148:149], v[156:157]
	s_nop 0
	v_cndmask_b32_e32 v48, v205, v48, vcc
	v_lshlrev_b32_e32 v180, 2, v48
	v_add_f32_e32 v48, v142, v143
	s_waitcnt lgkmcnt(0)
	v_mov_b32_e32 v142, v48
	s_nop 1
	v_permlane16_swap_b32_e32 v48, v142
	v_add_f32_e32 v143, v48, v142
	v_add_f32_e32 v48, v148, v149
	v_mov_b32_e32 v145, v143
	s_nop 1
	v_permlane32_swap_b32_e32 v143, v145
	s_waitcnt lgkmcnt(0)
	v_mov_b32_e32 v142, v48
	s_nop 1
	v_permlane16_swap_b32_e32 v48, v142
	v_add_f32_e32 v142, v48, v142
	v_mov_b32_e32 v144, v142
	s_nop 1
	v_permlane32_swap_b32_e32 v142, v144
	v_pk_add_f32 v[142:143], v[142:143], v[144:145]
	s_nop 0
	v_pk_fma_f32 v[158:159], v[142:143], s[36:37], v[154:155] op_sel_hi:[1,0,0]
	s_nop 0
	v_mul_f32_e32 v48, 0x4b800000, v159
	v_cmp_gt_f32_e32 vcc, s75, v159
	v_cmp_gt_f32_e64 s[42:43], s75, v158
	s_nop 0
	v_cndmask_b32_e32 v48, v159, v48, vcc
	v_rsq_f32_e32 v48, v48
	s_nop 0
	v_mul_f32_e32 v142, 0x45800000, v48
	v_cndmask_b32_e32 v48, v48, v142, vcc
	v_pk_add_f32 v[142:143], v[146:147], v[152:153]
	v_pk_mul_f32 v[126:127], v[126:127], v[48:49] op_sel_hi:[1,0]
	v_add_f32_e32 v142, v142, v143
	v_pk_mul_f32 v[122:123], v[122:123], v[48:49] op_sel_hi:[1,0]
	v_pk_mul_f32 v[128:129], v[128:129], v[48:49] op_sel_hi:[1,0]
	v_pk_mul_f32 v[124:125], v[124:125], v[48:49] op_sel_hi:[1,0]
	v_pk_mul_f32 v[120:121], v[120:121], v[48:49] op_sel_hi:[1,0]
	s_waitcnt lgkmcnt(0)
	v_mov_b32_e32 v143, v142
	s_nop 1
	v_permlane16_swap_b32_e32 v142, v143
	v_add_f32_e32 v153, v142, v143
	s_waitcnt vmcnt(16)
	v_pk_add_f32 v[142:143], v[150:151], v[160:161]
	v_pk_mul_f32 v[118:119], v[118:119], v[48:49] op_sel_hi:[1,0]
	v_add_f32_e32 v142, v142, v143
	v_pk_mul_f32 v[116:117], v[116:117], v[48:49] op_sel_hi:[1,0]
	v_pk_mul_f32 v[114:115], v[114:115], v[48:49] op_sel_hi:[1,0]
	v_mul_f32_e32 v48, v127, v127
	v_cvt_pk_bf16_f32 v160, v126, v127
	s_waitcnt lgkmcnt(0)
	v_mov_b32_e32 v143, v142
	s_nop 1
	v_permlane16_swap_b32_e32 v142, v143
	v_add_f32_e32 v152, v142, v143
	s_waitcnt vmcnt(12)
	v_pk_add_f32 v[142:143], v[162:163], v[166:167]
	v_cvt_pk_bf16_f32 v162, v122, v123
	v_add_f32_e32 v142, v142, v143
	v_mul_f32_e32 v123, v123, v123
	v_cvt_pk_bf16_f32 v161, v128, v129
	v_cvt_pk_bf16_f32 v163, v124, v125
	v_fmac_f32_e32 v48, v126, v126
	s_waitcnt lgkmcnt(0)
	v_mov_b32_e32 v143, v142
	s_nop 1
	v_permlane16_swap_b32_e32 v142, v143
	v_add_f32_e32 v149, v142, v143
	s_waitcnt vmcnt(8)
	v_pk_add_f32 v[142:143], v[164:165], v[168:169]
	v_mul_f32_e32 v126, v129, v129
	v_add_f32_e32 v142, v142, v143
	v_fmac_f32_e32 v123, v122, v122
	v_mul_f32_e32 v122, v125, v125
	v_fmac_f32_e32 v126, v128, v128
	v_fmac_f32_e32 v122, v124, v124
	s_waitcnt lgkmcnt(0)
	v_mov_b32_e32 v143, v142
	s_nop 1
	v_permlane16_swap_b32_e32 v142, v143
	v_add_f32_e32 v148, v142, v143
	s_waitcnt vmcnt(4)
	v_pk_add_f32 v[142:143], v[170:171], v[172:173]
	v_mov_b32_e32 v157, v153
	v_add_f32_e32 v142, v142, v143
	v_mov_b32_e32 v156, v152
	v_mov_b32_e32 v151, v149
	v_mov_b32_e32 v150, v148
	v_add_f32_e32 v48, v48, v126
	s_waitcnt lgkmcnt(0)
	v_mov_b32_e32 v143, v142
	s_nop 1
	v_permlane16_swap_b32_e32 v142, v143
	v_add_f32_e32 v145, v142, v143
	s_waitcnt vmcnt(0)
	v_pk_add_f32 v[142:143], v[182:183], v[184:185]
	v_mov_b32_e32 v147, v145
	v_add_f32_e32 v142, v142, v143
	v_add_f32_e32 v122, v123, v122
	v_permlane32_swap_b32_e32 v153, v157
	v_permlane32_swap_b32_e32 v152, v156
	s_waitcnt lgkmcnt(0)
	v_mov_b32_e32 v143, v142
	s_nop 1
	v_permlane16_swap_b32_e32 v142, v143
	v_add_f32_e32 v144, v142, v143
	v_lshl_or_b32 v142, s44, 8, v177
	v_mad_u64_u32 v[142:143], s[20:21], v179, s6, v[142:143]
	v_mov_b32_e32 v143, v49
	v_lshl_add_u64 v[164:165], v[142:143], 1, s[12:13]
	global_store_dwordx4 v[164:165], v[160:163], off
	s_nop 1
	v_cvt_pk_bf16_f32 v160, v118, v119
	v_cvt_pk_bf16_f32 v161, v120, v121
	v_cvt_pk_bf16_f32 v162, v114, v115
	v_cvt_pk_bf16_f32 v163, v116, v117
	v_lshl_add_u64 v[164:165], v[164:165], 0, s[34:35]
	global_store_dwordx4 v[164:165], v[160:163], off
	s_nop 1
	v_mov_b32_e32 v146, v144
	v_permlane32_swap_b32_e32 v149, v151
	v_permlane32_swap_b32_e32 v148, v150
	v_permlane32_swap_b32_e32 v145, v147
	v_permlane32_swap_b32_e32 v144, v146
	v_add_f32_e32 v48, v48, v122
	s_cbranch_scc1 .LBB0_591
	s_mov_b64 s[62:63], 0
	s_cmp_eq_u32 s44, 1
	s_mov_b64 s[60:61], 0
	s_cbranch_scc0 .LBB0_592
	ds_bpermute_b32 v122, v180, v48
	s_and_b64 s[60:61], s[40:41], exec
	s_waitcnt lgkmcnt(0)
	v_add_f32_e32 v122, v48, v122
	v_mov_b32_e32 v123, v122
	s_nop 1
	v_permlane32_swap_b32_e32 v122, v123
	s_branch .LBB0_592
